# mixer-A: the four spatial-weight tile loads issued together with counted waits instead of load-wait-write one at a time
# baseline (speedup 1.0000x reference)
.LBB0_923:
	s_mov_b64 s[4:5], 0
	v_mov_b32_e32 v0, v33
	s_add_u32 s10, s76, s4
	s_getreg_b32 s4, hwreg(HW_REG_HW_ID, 0, 6)
	s_addc_u32 s11, s77, s5
	s_lshl_b32 s4, s4, 2
	s_and_b32 s4, s4, 0xfc
	s_add_i32 s4, s4, 0
	s_add_i32 s4, s4, 0x21100
	v_mov_b32_e32 v1, s4
	ds_read_b32 v1, v1
	v_mbcnt_lo_u32_b32 v0, -1, v0
	v_mbcnt_hi_u32_b32 v0, -1, v0
	s_and_b32 s15, s13, 0xffffff80
	s_add_u32 s4, s10, 0x4bf51000
	s_waitcnt lgkmcnt(0)
	v_lshl_or_b32 v37, v1, 6, v0
	s_addc_u32 s5, s11, 0
	v_ashrrev_i32_e32 v18, 4, v37
	v_and_b32_e32 v1, 0x7f, v37
	v_and_b32_e32 v0, -8, v18
	s_ashr_i32 s6, s15, 31
	v_or_b32_e32 v2, s15, v1
	v_ashrrev_i32_e32 v1, 31, v0
	v_or_b32_e32 v6, 1, v0
	v_mov_b32_e32 v3, s6
	v_lshlrev_b64 v[4:5], 17, v[0:1]
	v_ashrrev_i32_e32 v7, 31, v6
	v_or_b32_e32 v8, 2, v0
	v_or_b32_e32 v10, 3, v0
	v_or_b32_e32 v12, 4, v0
	v_or_b32_e32 v14, 5, v0
	v_or_b32_e32 v0, 6, v0
	v_lshlrev_b64 v[2:3], 3, v[2:3]
	v_lshl_add_u64 v[4:5], s[4:5], 0, v[4:5]
	v_lshlrev_b64 v[6:7], 17, v[6:7]
	v_ashrrev_i32_e32 v9, 31, v8
	v_ashrrev_i32_e32 v13, 31, v12
	v_ashrrev_i32_e32 v1, 31, v0
	v_lshl_add_u64 v[4:5], v[4:5], 0, v[2:3]
	v_lshl_add_u64 v[6:7], s[4:5], 0, v[6:7]
	v_lshlrev_b64 v[8:9], 17, v[8:9]
	v_ashrrev_i32_e32 v11, 31, v10
	v_lshlrev_b64 v[12:13], 17, v[12:13]
	v_lshlrev_b64 v[0:1], 17, v[0:1]
	global_load_dwordx2 v[4:5], v[4:5], off
	v_lshl_add_u64 v[6:7], v[6:7], 0, v[2:3]
	v_lshl_add_u64 v[8:9], s[4:5], 0, v[8:9]
	v_lshlrev_b64 v[10:11], 17, v[10:11]
	v_lshl_add_u64 v[12:13], s[4:5], 0, v[12:13]
	v_lshl_add_u64 v[0:1], s[4:5], 0, v[0:1]
	global_load_dwordx2 v[6:7], v[6:7], off
	v_lshl_add_u64 v[8:9], v[8:9], 0, v[2:3]
	v_lshl_add_u64 v[10:11], s[4:5], 0, v[10:11]
	v_lshl_add_u64 v[12:13], v[12:13], 0, v[2:3]
	v_ashrrev_i32_e32 v15, 31, v14
	v_lshl_add_u64 v[0:1], v[0:1], 0, v[2:3]
	global_load_dwordx2 v[8:9], v[8:9], off
	v_lshl_add_u64 v[10:11], v[10:11], 0, v[2:3]
	global_load_dwordx2 v[12:13], v[12:13], off
	v_lshlrev_b64 v[14:15], 17, v[14:15]
	global_load_dwordx2 v[16:17], v[0:1], off
	v_or_b32_e32 v0, 7, v18
	global_load_dwordx2 v[10:11], v[10:11], off
	v_lshl_add_u64 v[14:15], s[4:5], 0, v[14:15]
	v_ashrrev_i32_e32 v1, 31, v0
	v_lshl_add_u64 v[14:15], v[14:15], 0, v[2:3]
	v_lshlrev_b64 v[0:1], 17, v[0:1]
	global_load_dwordx2 v[14:15], v[14:15], off
	v_lshl_add_u64 v[0:1], s[4:5], 0, v[0:1]
	v_lshl_add_u64 v[0:1], v[0:1], 0, v[2:3]
	global_load_dwordx2 v[2:3], v[0:1], off
	s_and_b32 s6, s14, 7
	s_or_b32 s60, s6, s12
	v_lshlrev_b32_e32 v24, 3, v37
	s_lshl_b64 s[4:5], s[60:61], 15
	v_add_u32_e32 v0, 0, v24
	s_add_u32 s4, s10, s4
	v_lshlrev_b32_e32 v1, 4, v37
	v_add_u32_e32 v0, 0x18400, v0
	s_addc_u32 s5, s11, s5
	v_and_b32_e32 v32, 0xf0, v1
	v_lshlrev_b32_e32 v1, 8, v18
	s_add_i32 s8, 0, 0x10000
	v_add_u32_e32 v43, 0x200, v37
	v_add_u32_e32 v41, 0x400, v37
	v_add_u32_e32 v39, 0x600, v37
	v_cmp_gt_i32_e32 vcc, s22, v37
	s_waitcnt vmcnt(0)
	v_pk_add_f32 v[4:5], v[4:5], 0 op_sel_hi:[1,0]
	s_nop 0
	v_pk_add_f32 v[4:5], v[4:5], v[6:7]
	s_nop 0
	v_pk_add_f32 v[4:5], v[4:5], v[8:9]
	v_xor_b32_e32 v8, v18, v37
	v_lshlrev_b32_e32 v8, 4, v8
	v_and_b32_e32 v8, 0xf0, v8
	v_add3_u32 v1, s8, v1, v8
	v_pk_add_f32 v[4:5], v[4:5], v[10:11]
	s_nop 0
	v_pk_add_f32 v[4:5], v[4:5], v[12:13]
	s_nop 0
	v_pk_add_f32 v[4:5], v[4:5], v[14:15]
	s_nop 0
	v_pk_add_f32 v[4:5], v[4:5], v[16:17]
	s_nop 0
	v_pk_add_f32 v[2:3], v[4:5], v[2:3]
	ds_write_b64 v0, v[2:3]
	v_lshl_add_u64 v[2:3], s[4:5], 0, v[32:33]
	s_mov_b64 s[4:5], 0x10e00000
	v_lshl_add_u64 v[6:7], v[2:3], 0, s[4:5]
	v_lshlrev_b32_e32 v2, 7, v18
	v_ashrrev_i32_e32 v3, 31, v2
	v_lshl_add_u64 v[2:3], v[2:3], 1, v[6:7]
	global_load_dwordx4 v[2:5], v[2:3], off
	v_ashrrev_i32_e32 v60, 4, v43
	v_lshlrev_b32_e32 v8, 7, v60
	v_ashrrev_i32_e32 v9, 31, v8
	v_lshl_add_u64 v[8:9], v[8:9], 1, v[6:7]
	global_load_dwordx4 v[48:51], v[8:9], off
	v_lshlrev_b32_e32 v63, 8, v60
	v_xor_b32_e32 v60, v60, v37
	v_lshlrev_b32_e32 v60, 4, v60
	v_and_b32_e32 v60, 0xf0, v60
	v_add3_u32 v60, s8, v63, v60
	v_ashrrev_i32_e32 v61, 4, v41
	v_lshlrev_b32_e32 v8, 7, v61
	v_ashrrev_i32_e32 v9, 31, v8
	v_lshl_add_u64 v[8:9], v[8:9], 1, v[6:7]
	global_load_dwordx4 v[52:55], v[8:9], off
	v_lshlrev_b32_e32 v63, 8, v61
	v_xor_b32_e32 v61, v61, v37
	v_lshlrev_b32_e32 v61, 4, v61
	v_and_b32_e32 v61, 0xf0, v61
	v_add3_u32 v61, s8, v63, v61
	v_ashrrev_i32_e32 v62, 4, v39
	v_lshlrev_b32_e32 v8, 7, v62
	v_ashrrev_i32_e32 v9, 31, v8
	v_lshl_add_u64 v[8:9], v[8:9], 1, v[6:7]
	global_load_dwordx4 v[56:59], v[8:9], off
	v_lshlrev_b32_e32 v63, 8, v62
	v_xor_b32_e32 v62, v62, v37
	v_lshlrev_b32_e32 v62, 4, v62
	v_and_b32_e32 v62, 0xf0, v62
	v_add3_u32 v62, s8, v63, v62
	s_waitcnt vmcnt(3)
	ds_write_b128 v1, v[2:5]
	s_waitcnt vmcnt(2)
	ds_write_b128 v60, v[48:51]
	s_waitcnt vmcnt(1)
	ds_write_b128 v61, v[52:55]
	s_waitcnt vmcnt(0)
	ds_write_b128 v62, v[56:59]
	s_waitcnt vmcnt(0) lgkmcnt(0)
	s_barrier
	s_and_saveexec_b64 s[4:5], vcc
	s_cbranch_execz .LBB0_922
	ds_read2st64_b64 v[2:5], v0 offset1:2
	s_mov_b32 s16, 0x3a000000
	v_lshlrev_b32_e32 v6, 1, v37
	s_waitcnt lgkmcnt(0)
	v_pk_add_f32 v[2:3], v[2:3], 0 op_sel_hi:[1,0]
	s_nop 0
	v_pk_add_f32 v[4:5], v[2:3], v[4:5]
	ds_read2st64_b64 v[0:3], v0 offset0:4 offset1:6
	s_waitcnt lgkmcnt(0)
	v_pk_add_f32 v[0:1], v[4:5], v[0:1]
	s_nop 0
	v_pk_add_f32 v[0:1], v[0:1], v[2:3]
	v_lshl_add_u32 v2, v6, 2, 0
	v_pk_mul_f32 v[0:1], v[0:1], s[16:17] op_sel_hi:[1,0]
	v_add_u32_e32 v2, 0x18000, v2
	v_fma_f32 v1, -v0, v0, v1
	v_max_f32_e32 v1, 0, v1
	v_add_f32_e32 v1, 0x358637bd, v1
	v_cmp_gt_f32_e32 vcc, s82, v1
	v_mul_f32_e32 v3, 0x4b800000, v1
	s_nop 0
	v_cndmask_b32_e32 v1, v1, v3, vcc
	v_rsq_f32_e32 v1, v1
	s_nop 0
	v_mul_f32_e32 v3, 0x45800000, v1
	v_cndmask_b32_e32 v1, v1, v3, vcc
	ds_write_b64 v2, v[0:1]
	s_branch .LBB0_922

.LBB0_931:
	s_mov_b64 s[8:9], 0
	v_mov_b32_e32 v0, v33
	s_add_u32 s12, s76, s8
	s_getreg_b32 s8, hwreg(HW_REG_HW_ID, 0, 6)
	s_addc_u32 s13, s77, s9
	s_lshl_b32 s8, s8, 2
	s_and_b32 s8, s8, 0xfc
	s_add_i32 s8, s8, 0
	s_add_i32 s8, s8, 0x21100
	v_mov_b32_e32 v1, s8
	ds_read_b32 v1, v1
	v_mbcnt_lo_u32_b32 v0, -1, v0
	v_mbcnt_hi_u32_b32 v0, -1, v0
	s_add_i32 s8, s87, s14
	s_and_b32 s15, s8, 0xffffff80
	s_waitcnt lgkmcnt(0)
	v_lshl_or_b32 v41, v1, 6, v0
	s_add_u32 s8, s12, 0x4bf51000
	v_ashrrev_i32_e32 v18, 4, v41
	v_and_b32_e32 v1, 0x7f, v41
	v_and_b32_e32 v0, -8, v18
	s_addc_u32 s9, s13, 0
	s_ashr_i32 s10, s15, 31
	v_or_b32_e32 v2, s15, v1
	v_ashrrev_i32_e32 v1, 31, v0
	v_or_b32_e32 v6, 1, v0
	v_mov_b32_e32 v3, s10
	v_lshlrev_b64 v[4:5], 17, v[0:1]
	v_ashrrev_i32_e32 v7, 31, v6
	v_or_b32_e32 v8, 2, v0
	v_or_b32_e32 v10, 3, v0
	v_or_b32_e32 v12, 4, v0
	v_or_b32_e32 v14, 5, v0
	v_or_b32_e32 v0, 6, v0
	v_lshlrev_b64 v[2:3], 3, v[2:3]
	v_lshl_add_u64 v[4:5], s[8:9], 0, v[4:5]
	v_lshlrev_b64 v[6:7], 17, v[6:7]
	v_ashrrev_i32_e32 v9, 31, v8
	v_ashrrev_i32_e32 v13, 31, v12
	v_ashrrev_i32_e32 v1, 31, v0
	v_lshl_add_u64 v[4:5], v[4:5], 0, v[2:3]
	v_lshl_add_u64 v[6:7], s[8:9], 0, v[6:7]
	v_lshlrev_b64 v[8:9], 17, v[8:9]
	v_ashrrev_i32_e32 v11, 31, v10
	v_lshlrev_b64 v[12:13], 17, v[12:13]
	v_lshlrev_b64 v[0:1], 17, v[0:1]
	global_load_dwordx2 v[4:5], v[4:5], off
	v_lshl_add_u64 v[6:7], v[6:7], 0, v[2:3]
	v_lshl_add_u64 v[8:9], s[8:9], 0, v[8:9]
	v_lshlrev_b64 v[10:11], 17, v[10:11]
	v_lshl_add_u64 v[12:13], s[8:9], 0, v[12:13]
	v_lshl_add_u64 v[0:1], s[8:9], 0, v[0:1]
	global_load_dwordx2 v[6:7], v[6:7], off
	v_lshl_add_u64 v[8:9], v[8:9], 0, v[2:3]
	v_lshl_add_u64 v[10:11], s[8:9], 0, v[10:11]
	v_lshl_add_u64 v[12:13], v[12:13], 0, v[2:3]
	v_ashrrev_i32_e32 v15, 31, v14
	v_lshl_add_u64 v[0:1], v[0:1], 0, v[2:3]
	global_load_dwordx2 v[8:9], v[8:9], off
	v_lshl_add_u64 v[10:11], v[10:11], 0, v[2:3]
	global_load_dwordx2 v[12:13], v[12:13], off
	v_lshlrev_b64 v[14:15], 17, v[14:15]
	global_load_dwordx2 v[16:17], v[0:1], off
	v_or_b32_e32 v0, 7, v18
	global_load_dwordx2 v[10:11], v[10:11], off
	v_lshl_add_u64 v[14:15], s[8:9], 0, v[14:15]
	v_ashrrev_i32_e32 v1, 31, v0
	v_lshl_add_u64 v[14:15], v[14:15], 0, v[2:3]
	v_lshlrev_b64 v[0:1], 17, v[0:1]
	global_load_dwordx2 v[14:15], v[14:15], off
	v_lshl_add_u64 v[0:1], s[8:9], 0, v[0:1]
	v_lshl_add_u64 v[0:1], v[0:1], 0, v[2:3]
	global_load_dwordx2 v[2:3], v[0:1], off
	v_lshlrev_b32_e32 v24, 3, v41
	v_add_u32_e32 v0, 0, v24
	s_add_u32 s8, s12, s2
	v_lshlrev_b32_e32 v1, 4, v41
	v_add_u32_e32 v0, 0x18400, v0
	s_addc_u32 s9, s13, s3
	v_and_b32_e32 v32, 0xf0, v1
	v_lshlrev_b32_e32 v1, 8, v18
	s_add_i32 s10, 0, 0x10000
	v_add_u32_e32 v47, 0x200, v41
	v_add_u32_e32 v46, 0x400, v41
	v_add_u32_e32 v43, 0x600, v41
	v_cmp_gt_i32_e32 vcc, s22, v41
	s_waitcnt vmcnt(0)
	v_pk_add_f32 v[4:5], v[4:5], 0 op_sel_hi:[1,0]
	s_nop 0
	v_pk_add_f32 v[4:5], v[4:5], v[6:7]
	s_nop 0
	v_pk_add_f32 v[4:5], v[4:5], v[8:9]
	v_xor_b32_e32 v8, v18, v41
	v_lshlrev_b32_e32 v8, 4, v8
	v_and_b32_e32 v8, 0xf0, v8
	v_add3_u32 v1, s10, v1, v8
	v_pk_add_f32 v[4:5], v[4:5], v[10:11]
	s_nop 0
	v_pk_add_f32 v[4:5], v[4:5], v[12:13]
	s_nop 0
	v_pk_add_f32 v[4:5], v[4:5], v[14:15]
	s_nop 0
	v_pk_add_f32 v[4:5], v[4:5], v[16:17]
	s_nop 0
	v_pk_add_f32 v[2:3], v[4:5], v[2:3]
	ds_write_b64 v0, v[2:3]
	v_lshl_add_u64 v[2:3], s[8:9], 0, v[32:33]
	s_mov_b64 s[8:9], 0x10e00000
	v_lshl_add_u64 v[6:7], v[2:3], 0, s[8:9]
	v_lshlrev_b32_e32 v2, 7, v18
	v_ashrrev_i32_e32 v3, 31, v2
	v_lshl_add_u64 v[2:3], v[2:3], 1, v[6:7]
	global_load_dwordx4 v[2:5], v[2:3], off
	v_ashrrev_i32_e32 v60, 4, v47
	v_lshlrev_b32_e32 v8, 7, v60
	v_ashrrev_i32_e32 v9, 31, v8
	v_lshl_add_u64 v[8:9], v[8:9], 1, v[6:7]
	global_load_dwordx4 v[48:51], v[8:9], off
	v_lshlrev_b32_e32 v63, 8, v60
	v_xor_b32_e32 v60, v60, v41
	v_lshlrev_b32_e32 v60, 4, v60
	v_and_b32_e32 v60, 0xf0, v60
	v_add3_u32 v60, s10, v63, v60
	v_ashrrev_i32_e32 v61, 4, v46
	v_lshlrev_b32_e32 v8, 7, v61
	v_ashrrev_i32_e32 v9, 31, v8
	v_lshl_add_u64 v[8:9], v[8:9], 1, v[6:7]
	global_load_dwordx4 v[52:55], v[8:9], off
	v_lshlrev_b32_e32 v63, 8, v61
	v_xor_b32_e32 v61, v61, v41
	v_lshlrev_b32_e32 v61, 4, v61
	v_and_b32_e32 v61, 0xf0, v61
	v_add3_u32 v61, s10, v63, v61
	v_ashrrev_i32_e32 v62, 4, v43
	v_lshlrev_b32_e32 v8, 7, v62
	v_ashrrev_i32_e32 v9, 31, v8
	v_lshl_add_u64 v[8:9], v[8:9], 1, v[6:7]
	global_load_dwordx4 v[56:59], v[8:9], off
	v_lshlrev_b32_e32 v63, 8, v62
	v_xor_b32_e32 v62, v62, v41
	v_lshlrev_b32_e32 v62, 4, v62
	v_and_b32_e32 v62, 0xf0, v62
	v_add3_u32 v62, s10, v63, v62
	s_waitcnt vmcnt(3)
	ds_write_b128 v1, v[2:5]
	s_waitcnt vmcnt(2)
	ds_write_b128 v60, v[48:51]
	s_waitcnt vmcnt(1)
	ds_write_b128 v61, v[52:55]
	s_waitcnt vmcnt(0)
	ds_write_b128 v62, v[56:59]
	s_waitcnt vmcnt(0) lgkmcnt(0)
	s_barrier
	s_and_saveexec_b64 s[8:9], vcc
	s_cbranch_execz .LBB0_930
	ds_read2st64_b64 v[2:5], v0 offset1:2
	s_mov_b32 s16, 0x3a000000
	v_lshlrev_b32_e32 v6, 1, v41
	s_waitcnt lgkmcnt(0)
	v_pk_add_f32 v[2:3], v[2:3], 0 op_sel_hi:[1,0]
	s_nop 0
	v_pk_add_f32 v[4:5], v[2:3], v[4:5]
	ds_read2st64_b64 v[0:3], v0 offset0:4 offset1:6
	s_waitcnt lgkmcnt(0)
	v_pk_add_f32 v[0:1], v[4:5], v[0:1]
	s_nop 0
	v_pk_add_f32 v[0:1], v[0:1], v[2:3]
	v_lshl_add_u32 v2, v6, 2, 0
	v_pk_mul_f32 v[0:1], v[0:1], s[16:17] op_sel_hi:[1,0]
	v_add_u32_e32 v2, 0x18000, v2
	v_fma_f32 v1, -v0, v0, v1
	v_max_f32_e32 v1, 0, v1
	v_add_f32_e32 v1, 0x358637bd, v1
	v_cmp_gt_f32_e32 vcc, s82, v1
	v_mul_f32_e32 v3, 0x4b800000, v1
	s_nop 0
	v_cndmask_b32_e32 v1, v1, v3, vcc
	v_rsq_f32_e32 v1, v1
	s_nop 0
	v_mul_f32_e32 v3, 0x45800000, v1
	v_cndmask_b32_e32 v1, v1, v3, vcc
	ds_write_b64 v2, v[0:1]
	s_branch .LBB0_930

.LBB0_934:
	s_and_b64 vcc, exec, s[2:3]
	s_cbranch_vccz .LBB0_938
	s_mov_b64 s[2:3], 0
	v_mov_b32_e32 v0, v33
	s_add_u32 s6, s76, s2
	s_getreg_b32 s2, hwreg(HW_REG_HW_ID, 0, 6)
	s_addc_u32 s7, s77, s3
	s_lshl_b32 s2, s2, 2
	s_and_b32 s2, s2, 0xfc
	s_add_i32 s2, s2, 0
	s_add_i32 s2, s2, 0x21100
	v_mov_b32_e32 v1, s2
	ds_read_b32 v1, v1
	v_mbcnt_lo_u32_b32 v0, -1, v0
	v_mbcnt_hi_u32_b32 v0, -1, v0
	v_readlane_b32 s4, v254, 35
	s_add_u32 s2, s6, 0x4bf51000
	s_waitcnt lgkmcnt(0)
	v_lshl_or_b32 v41, v1, 6, v0
	s_addc_u32 s3, s7, 0
	v_ashrrev_i32_e32 v18, 4, v41
	v_and_b32_e32 v1, 0x7f, v41
	v_and_b32_e32 v0, -8, v18
	v_or_b32_e32 v2, s4, v1
	v_readlane_b32 s4, v254, 36
	v_ashrrev_i32_e32 v1, 31, v0
	v_or_b32_e32 v6, 1, v0
	v_mov_b32_e32 v3, s4
	v_lshlrev_b64 v[4:5], 17, v[0:1]
	v_ashrrev_i32_e32 v7, 31, v6
	v_or_b32_e32 v8, 2, v0
	v_or_b32_e32 v10, 3, v0
	v_or_b32_e32 v12, 4, v0
	v_or_b32_e32 v14, 5, v0
	v_or_b32_e32 v0, 6, v0
	v_lshlrev_b64 v[2:3], 3, v[2:3]
	v_lshl_add_u64 v[4:5], s[2:3], 0, v[4:5]
	v_lshlrev_b64 v[6:7], 17, v[6:7]
	v_ashrrev_i32_e32 v9, 31, v8
	v_ashrrev_i32_e32 v13, 31, v12
	v_ashrrev_i32_e32 v1, 31, v0
	v_lshl_add_u64 v[4:5], v[4:5], 0, v[2:3]
	v_lshl_add_u64 v[6:7], s[2:3], 0, v[6:7]
	v_lshlrev_b64 v[8:9], 17, v[8:9]
	v_ashrrev_i32_e32 v11, 31, v10
	v_lshlrev_b64 v[12:13], 17, v[12:13]
	v_lshlrev_b64 v[0:1], 17, v[0:1]
	global_load_dwordx2 v[4:5], v[4:5], off
	v_lshl_add_u64 v[6:7], v[6:7], 0, v[2:3]
	v_lshl_add_u64 v[8:9], s[2:3], 0, v[8:9]
	v_lshlrev_b64 v[10:11], 17, v[10:11]
	v_lshl_add_u64 v[12:13], s[2:3], 0, v[12:13]
	v_lshl_add_u64 v[0:1], s[2:3], 0, v[0:1]
	global_load_dwordx2 v[6:7], v[6:7], off
	v_lshl_add_u64 v[8:9], v[8:9], 0, v[2:3]
	v_lshl_add_u64 v[10:11], s[2:3], 0, v[10:11]
	v_lshl_add_u64 v[12:13], v[12:13], 0, v[2:3]
	v_ashrrev_i32_e32 v15, 31, v14
	v_lshl_add_u64 v[0:1], v[0:1], 0, v[2:3]
	global_load_dwordx2 v[8:9], v[8:9], off
	v_lshl_add_u64 v[10:11], v[10:11], 0, v[2:3]
	global_load_dwordx2 v[12:13], v[12:13], off
	v_lshlrev_b64 v[14:15], 17, v[14:15]
	global_load_dwordx2 v[16:17], v[0:1], off
	v_or_b32_e32 v0, 7, v18
	global_load_dwordx2 v[10:11], v[10:11], off
	v_lshl_add_u64 v[14:15], s[2:3], 0, v[14:15]
	v_ashrrev_i32_e32 v1, 31, v0
	v_lshl_add_u64 v[14:15], v[14:15], 0, v[2:3]
	v_lshlrev_b64 v[0:1], 17, v[0:1]
	global_load_dwordx2 v[14:15], v[14:15], off
	v_lshl_add_u64 v[0:1], s[2:3], 0, v[0:1]
	v_lshl_add_u64 v[0:1], v[0:1], 0, v[2:3]
	global_load_dwordx2 v[2:3], v[0:1], off
	s_lshl_b32 s2, s34, 3
	v_readlane_b32 s3, v254, 6
	s_or_b32 s60, s2, s3
	v_lshlrev_b32_e32 v24, 3, v41
	s_lshl_b64 s[2:3], s[60:61], 15
	v_add_u32_e32 v0, 0, v24
	s_add_u32 s2, s6, s2
	v_lshlrev_b32_e32 v1, 4, v41
	v_add_u32_e32 v0, 0x18400, v0
	s_addc_u32 s3, s7, s3
	v_and_b32_e32 v32, 0xf0, v1
	v_lshlrev_b32_e32 v1, 8, v18
	s_add_i32 s4, 0, 0x10000
	v_add_u32_e32 v47, 0x200, v41
	v_add_u32_e32 v46, 0x400, v41
	v_add_u32_e32 v43, 0x600, v41
	v_cmp_gt_i32_e32 vcc, s22, v41
	s_waitcnt vmcnt(0)
	v_pk_add_f32 v[4:5], v[4:5], 0 op_sel_hi:[1,0]
	s_nop 0
	v_pk_add_f32 v[4:5], v[4:5], v[6:7]
	s_nop 0
	v_pk_add_f32 v[4:5], v[4:5], v[8:9]
	v_xor_b32_e32 v8, v18, v41
	v_lshlrev_b32_e32 v8, 4, v8
	v_and_b32_e32 v8, 0xf0, v8
	v_add3_u32 v1, s4, v1, v8
	v_pk_add_f32 v[4:5], v[4:5], v[10:11]
	s_nop 0
	v_pk_add_f32 v[4:5], v[4:5], v[12:13]
	s_nop 0
	v_pk_add_f32 v[4:5], v[4:5], v[14:15]
	s_nop 0
	v_pk_add_f32 v[4:5], v[4:5], v[16:17]
	s_nop 0
	v_pk_add_f32 v[2:3], v[4:5], v[2:3]
	ds_write_b64 v0, v[2:3]
	v_lshl_add_u64 v[2:3], s[2:3], 0, v[32:33]
	s_mov_b64 s[2:3], 0x10e00000
	v_lshl_add_u64 v[6:7], v[2:3], 0, s[2:3]
	v_lshlrev_b32_e32 v2, 7, v18
	v_ashrrev_i32_e32 v3, 31, v2
	v_lshl_add_u64 v[2:3], v[2:3], 1, v[6:7]
	global_load_dwordx4 v[2:5], v[2:3], off
	v_ashrrev_i32_e32 v60, 4, v47
	v_lshlrev_b32_e32 v8, 7, v60
	v_ashrrev_i32_e32 v9, 31, v8
	v_lshl_add_u64 v[8:9], v[8:9], 1, v[6:7]
	global_load_dwordx4 v[48:51], v[8:9], off
	v_lshlrev_b32_e32 v63, 8, v60
	v_xor_b32_e32 v60, v60, v41
	v_lshlrev_b32_e32 v60, 4, v60
	v_and_b32_e32 v60, 0xf0, v60
	v_add3_u32 v60, s4, v63, v60
	v_ashrrev_i32_e32 v61, 4, v46
	v_lshlrev_b32_e32 v8, 7, v61
	v_ashrrev_i32_e32 v9, 31, v8
	v_lshl_add_u64 v[8:9], v[8:9], 1, v[6:7]
	global_load_dwordx4 v[52:55], v[8:9], off
	v_lshlrev_b32_e32 v63, 8, v61
	v_xor_b32_e32 v61, v61, v41
	v_lshlrev_b32_e32 v61, 4, v61
	v_and_b32_e32 v61, 0xf0, v61
	v_add3_u32 v61, s4, v63, v61
	v_ashrrev_i32_e32 v62, 4, v43
	v_lshlrev_b32_e32 v8, 7, v62
	v_ashrrev_i32_e32 v9, 31, v8
	v_lshl_add_u64 v[8:9], v[8:9], 1, v[6:7]
	global_load_dwordx4 v[56:59], v[8:9], off
	v_lshlrev_b32_e32 v63, 8, v62
	v_xor_b32_e32 v62, v62, v41
	v_lshlrev_b32_e32 v62, 4, v62
	v_and_b32_e32 v62, 0xf0, v62
	v_add3_u32 v62, s4, v63, v62
	s_waitcnt vmcnt(3)
	ds_write_b128 v1, v[2:5]
	s_waitcnt vmcnt(2)
	ds_write_b128 v60, v[48:51]
	s_waitcnt vmcnt(1)
	ds_write_b128 v61, v[52:55]
	s_waitcnt vmcnt(0)
	ds_write_b128 v62, v[56:59]
	s_waitcnt vmcnt(0) lgkmcnt(0)
	s_barrier
	s_and_saveexec_b64 s[2:3], vcc
	s_cbranch_execz .LBB0_937
	ds_read2st64_b64 v[2:5], v0 offset1:2
	s_mov_b32 s8, 0x3a000000
	v_lshlrev_b32_e32 v6, 1, v41
	s_waitcnt lgkmcnt(0)
	v_pk_add_f32 v[2:3], v[2:3], 0 op_sel_hi:[1,0]
	s_nop 0
	v_pk_add_f32 v[4:5], v[2:3], v[4:5]
	ds_read2st64_b64 v[0:3], v0 offset0:4 offset1:6
	s_waitcnt lgkmcnt(0)
	v_pk_add_f32 v[0:1], v[4:5], v[0:1]
	s_nop 0
	v_pk_add_f32 v[0:1], v[0:1], v[2:3]
	v_lshl_add_u32 v2, v6, 2, 0
	v_pk_mul_f32 v[0:1], v[0:1], s[8:9] op_sel_hi:[1,0]
	v_add_u32_e32 v2, 0x18000, v2
	v_fma_f32 v1, -v0, v0, v1
	v_max_f32_e32 v1, 0, v1
	v_add_f32_e32 v1, 0x358637bd, v1
	v_cmp_gt_f32_e32 vcc, s82, v1
	v_mul_f32_e32 v3, 0x4b800000, v1
	s_nop 0
	v_cndmask_b32_e32 v1, v1, v3, vcc
	v_rsq_f32_e32 v1, v1
	s_nop 0
	v_mul_f32_e32 v3, 0x45800000, v1
	v_cndmask_b32_e32 v1, v1, v3, vcc
	ds_write_b64 v2, v[0:1]
